# grid barrier: non-leader workgroups poll the top-level generation word directly instead of waiting for their XCD leader to relay it (one hop less per seam)
# baseline (speedup 1.0000x reference)
; __device__ __forceinline__ unsigned xb_ld(unsigned* p)              { return __hip_atomic_load(p, __ATOMIC_RELAXED, __HIP_MEMORY_SCOPE_AGENT); }
; __device__ __forceinline__ unsigned xb_add(unsigned* p, unsigned v) { return __hip_atomic_fetch_add(p, v, __ATOMIC_RELAXED, __HIP_MEMORY_SCOPE_AGENT); }
; #define XB_SPIN(cond, bar) do { unsigned _sp = 0; while (cond) { __builtin_amdgcn_s_sleep(1); \
;     if ((++_sp & 255u) == 0u) { if (xb_ld(&(bar)[XB_TMO])) break; if (_sp > XB_SPIN_CAP) { atomicAdd(&(bar)[XB_TMO], 1u); break; } } } } while (0)
; __device__ __forceinline__ void xcd_barrier(const XcdBarrier& b) {
;     ...
;         const unsigned old = xb_add(&bar[XB_XSUB(b.x)], 1u);
;         const unsigned gen = old / nloc;
;         if (old + 1u == (gen + 1u) * nloc) {
;             __builtin_amdgcn_fence(__ATOMIC_RELEASE, "agent");
;             asm volatile("s_waitcnt vmcnt(0)" ::: "memory");
;             const unsigned og = xb_add(&bar[XB_TOP], 1u);
;             const unsigned tg = og / nx;
;             if (og + 1u == (tg + 1u) * nx) xb_add(&bar[XB_TOPGEN], 1u);
;             else XB_SPIN(xb_ld(&bar[XB_TOPGEN]) == tg, bar);
;             __builtin_amdgcn_fence(__ATOMIC_ACQUIRE, "agent");
;             xb_add(&bar[XB_XGEN(b.x)], 1u);
;             asm volatile("s_waitcnt vmcnt(0)" ::: "memory");
;         } else {
;             XB_SPIN(xb_ld(&bar[XB_XGEN(b.x)]) == gen, bar);
.LBB0_151:
	s_lshl_b32 s6, s65, 8
	v_readlane_b32 s8, v247, 16
	v_readlane_b32 s9, v247, 17
	s_add_u32 s6, s8, s6
	s_addc_u32 s7, s9, 0
	v_mov_b32_e32 v1, 0x1000
	v_mov_b32_e32 v3, 1
	global_atomic_add v3, v1, v3, s[6:7] offset:1024 sc0
	v_cvt_f32_u32_e32 v1, v2
	v_sub_u32_e32 v4, 0, v2
	v_rcp_iflag_f32_e32 v1, v1
	s_nop 0
	v_mul_f32_e32 v1, 0x4f7ffffe, v1
	v_cvt_u32_f32_e32 v1, v1
	v_mul_lo_u32 v4, v4, v1
	v_mul_hi_u32 v4, v1, v4
	v_add_u32_e32 v1, v1, v4
	s_waitcnt vmcnt(0)
	v_mul_hi_u32 v1, v3, v1
	v_mul_lo_u32 v4, v1, v2
	v_sub_u32_e32 v4, v3, v4
	v_add_u32_e32 v5, 1, v1
	v_cmp_ge_u32_e32 vcc, v4, v2
	v_add_u32_e32 v3, 1, v3
	s_nop 0
	v_cndmask_b32_e32 v1, v1, v5, vcc
	v_sub_u32_e32 v5, v4, v2
	v_cndmask_b32_e32 v4, v4, v5, vcc
	v_add_u32_e32 v5, 1, v1
	v_cmp_ge_u32_e32 vcc, v4, v2
	s_nop 1
	v_cndmask_b32_e32 v1, v1, v5, vcc
	v_mul_lo_u32 v4, v2, v1
	v_add_u32_e32 v2, v4, v2
	v_cmp_ne_u32_e32 vcc, v3, v2
	s_and_saveexec_b64 s[8:9], vcc
	s_xor_b64 s[8:9], exec, s[8:9]
	s_cbranch_execz .LBB0_165
	s_waitcnt lgkmcnt(0)
	s_lshl_b32 s98, s65, 8
	s_sub_u32 s14, s6, s98
	s_subb_u32 s15, s7, 0
	s_add_u32 s14, s14, 0x3500
	s_addc_u32 s15, s15, 0
	v_mov_b32_e32 v0, 0
	global_load_dword v0, v0, s[14:15] sc1
	s_waitcnt vmcnt(0)
	v_cmp_eq_u32_e32 vcc, v0, v1
	s_and_saveexec_b64 s[10:11], vcc
	s_cbranch_execz .LBB0_164
	s_add_u32 s12, s84, 0xc0200
	s_addc_u32 s13, s85, 0
	s_mov_b32 s26, 1
	s_mov_b64 s[16:17], 0
	v_mov_b32_e32 v0, 0
	s_branch .LBB0_155

; __device__ __forceinline__ unsigned xb_ld(unsigned* p)              { return __hip_atomic_load(p, __ATOMIC_RELAXED, __HIP_MEMORY_SCOPE_AGENT); }
; __device__ __forceinline__ unsigned xb_add(unsigned* p, unsigned v) { return __hip_atomic_fetch_add(p, v, __ATOMIC_RELAXED, __HIP_MEMORY_SCOPE_AGENT); }
; #define XB_SPIN(cond, bar) do { unsigned _sp = 0; while (cond) { __builtin_amdgcn_s_sleep(1); \
;     if ((++_sp & 255u) == 0u) { if (xb_ld(&(bar)[XB_TMO])) break; if (_sp > XB_SPIN_CAP) { atomicAdd(&(bar)[XB_TMO], 1u); break; } } } } while (0)
; __device__ __forceinline__ void xcd_barrier(const XcdBarrier& b) {
;     ...
;         const unsigned old = xb_add(&bar[XB_XSUB(b.x)], 1u);
;         const unsigned gen = old / nloc;
;         if (old + 1u == (gen + 1u) * nloc) {
;             __builtin_amdgcn_fence(__ATOMIC_RELEASE, "agent");
;             asm volatile("s_waitcnt vmcnt(0)" ::: "memory");
;             const unsigned og = xb_add(&bar[XB_TOP], 1u);
;             const unsigned tg = og / nx;
;             if (og + 1u == (tg + 1u) * nx) xb_add(&bar[XB_TOPGEN], 1u);
;             else XB_SPIN(xb_ld(&bar[XB_TOPGEN]) == tg, bar);
;             __builtin_amdgcn_fence(__ATOMIC_ACQUIRE, "agent");
;             xb_add(&bar[XB_XGEN(b.x)], 1u);
;             asm volatile("s_waitcnt vmcnt(0)" ::: "memory");
;         } else {
;             XB_SPIN(xb_ld(&bar[XB_XGEN(b.x)]) == gen, bar);
.LBB0_211:
	s_lshl_b32 s6, s65, 8
	v_readlane_b32 s8, v247, 16
	v_readlane_b32 s9, v247, 17
	s_add_u32 s6, s8, s6
	s_addc_u32 s7, s9, 0
	v_mov_b32_e32 v1, 0x1000
	v_mov_b32_e32 v3, 1
	global_atomic_add v3, v1, v3, s[6:7] offset:1024 sc0
	v_cvt_f32_u32_e32 v1, v2
	v_sub_u32_e32 v4, 0, v2
	v_rcp_iflag_f32_e32 v1, v1
	s_nop 0
	v_mul_f32_e32 v1, 0x4f7ffffe, v1
	v_cvt_u32_f32_e32 v1, v1
	v_mul_lo_u32 v4, v4, v1
	v_mul_hi_u32 v4, v1, v4
	v_add_u32_e32 v1, v1, v4
	s_waitcnt vmcnt(0)
	v_mul_hi_u32 v1, v3, v1
	v_mul_lo_u32 v4, v1, v2
	v_sub_u32_e32 v4, v3, v4
	v_add_u32_e32 v5, 1, v1
	v_cmp_ge_u32_e32 vcc, v4, v2
	v_add_u32_e32 v3, 1, v3
	s_nop 0
	v_cndmask_b32_e32 v1, v1, v5, vcc
	v_sub_u32_e32 v5, v4, v2
	v_cndmask_b32_e32 v4, v4, v5, vcc
	v_add_u32_e32 v5, 1, v1
	v_cmp_ge_u32_e32 vcc, v4, v2
	s_nop 1
	v_cndmask_b32_e32 v1, v1, v5, vcc
	v_mul_lo_u32 v4, v2, v1
	v_add_u32_e32 v2, v4, v2
	v_cmp_ne_u32_e32 vcc, v3, v2
	s_and_saveexec_b64 s[8:9], vcc
	s_xor_b64 s[8:9], exec, s[8:9]
	s_cbranch_execz .LBB0_225
	s_waitcnt lgkmcnt(0)
	s_lshl_b32 s98, s65, 8
	s_sub_u32 s16, s6, s98
	s_subb_u32 s17, s7, 0
	s_add_u32 s16, s16, 0x3500
	s_addc_u32 s17, s17, 0
	v_mov_b32_e32 v0, 0
	global_load_dword v0, v0, s[16:17] sc1
	s_waitcnt vmcnt(0)
	v_cmp_eq_u32_e32 vcc, v0, v1
	s_and_saveexec_b64 s[10:11], vcc
	s_cbranch_execz .LBB0_224
	s_add_u32 s14, s84, 0xc0200
	s_addc_u32 s15, s85, 0
	s_mov_b32 s28, 1
	s_mov_b64 s[18:19], 0
	v_mov_b32_e32 v0, 0
	s_branch .LBB0_215

; __device__ __forceinline__ unsigned xb_ld(unsigned* p)              { return __hip_atomic_load(p, __ATOMIC_RELAXED, __HIP_MEMORY_SCOPE_AGENT); }
; __device__ __forceinline__ unsigned xb_add(unsigned* p, unsigned v) { return __hip_atomic_fetch_add(p, v, __ATOMIC_RELAXED, __HIP_MEMORY_SCOPE_AGENT); }
; #define XB_SPIN(cond, bar) do { unsigned _sp = 0; while (cond) { __builtin_amdgcn_s_sleep(1); \
;     if ((++_sp & 255u) == 0u) { if (xb_ld(&(bar)[XB_TMO])) break; if (_sp > XB_SPIN_CAP) { atomicAdd(&(bar)[XB_TMO], 1u); break; } } } } while (0)
; __device__ __forceinline__ void xcd_barrier(const XcdBarrier& b) {
;     ...
;         const unsigned old = xb_add(&bar[XB_XSUB(b.x)], 1u);
;         const unsigned gen = old / nloc;
;         if (old + 1u == (gen + 1u) * nloc) {
;             __builtin_amdgcn_fence(__ATOMIC_RELEASE, "agent");
;             asm volatile("s_waitcnt vmcnt(0)" ::: "memory");
;             const unsigned og = xb_add(&bar[XB_TOP], 1u);
;             const unsigned tg = og / nx;
;             if (og + 1u == (tg + 1u) * nx) xb_add(&bar[XB_TOPGEN], 1u);
;             else XB_SPIN(xb_ld(&bar[XB_TOPGEN]) == tg, bar);
;             __builtin_amdgcn_fence(__ATOMIC_ACQUIRE, "agent");
;             xb_add(&bar[XB_XGEN(b.x)], 1u);
;             asm volatile("s_waitcnt vmcnt(0)" ::: "memory");
;         } else {
;             XB_SPIN(xb_ld(&bar[XB_XGEN(b.x)]) == gen, bar);
.LBB0_346:
	s_lshl_b32 s6, s65, 8
	s_add_u32 s6, s88, s6
	s_addc_u32 s7, s89, 0
	v_mov_b32_e32 v1, 0x1000
	v_mov_b32_e32 v3, 1
	global_atomic_add v3, v1, v3, s[6:7] offset:1024 sc0
	v_cvt_f32_u32_e32 v1, v2
	v_sub_u32_e32 v4, 0, v2
	v_rcp_iflag_f32_e32 v1, v1
	s_nop 0
	v_mul_f32_e32 v1, 0x4f7ffffe, v1
	v_cvt_u32_f32_e32 v1, v1
	v_mul_lo_u32 v4, v4, v1
	v_mul_hi_u32 v4, v1, v4
	v_add_u32_e32 v1, v1, v4
	s_waitcnt vmcnt(0)
	v_mul_hi_u32 v1, v3, v1
	v_mul_lo_u32 v4, v1, v2
	v_sub_u32_e32 v4, v3, v4
	v_add_u32_e32 v5, 1, v1
	v_cmp_ge_u32_e32 vcc, v4, v2
	v_add_u32_e32 v3, 1, v3
	s_nop 0
	v_cndmask_b32_e32 v1, v1, v5, vcc
	v_sub_u32_e32 v5, v4, v2
	v_cndmask_b32_e32 v4, v4, v5, vcc
	v_add_u32_e32 v5, 1, v1
	v_cmp_ge_u32_e32 vcc, v4, v2
	s_nop 1
	v_cndmask_b32_e32 v1, v1, v5, vcc
	v_mul_lo_u32 v4, v2, v1
	v_add_u32_e32 v2, v4, v2
	v_cmp_ne_u32_e32 vcc, v3, v2
	s_and_saveexec_b64 s[8:9], vcc
	s_xor_b64 s[8:9], exec, s[8:9]
	s_cbranch_execz .LBB0_360
	s_waitcnt lgkmcnt(0)
	s_lshl_b32 s98, s65, 8
	s_sub_u32 s20, s6, s98
	s_subb_u32 s21, s7, 0
	s_add_u32 s20, s20, 0x3500
	s_addc_u32 s21, s21, 0
	v_mov_b32_e32 v0, 0
	global_load_dword v0, v0, s[20:21] sc1
	s_waitcnt vmcnt(0)
	v_cmp_eq_u32_e32 vcc, v0, v1
	s_and_saveexec_b64 s[10:11], vcc
	s_cbranch_execz .LBB0_359
	s_add_u32 s18, s84, 0xc0200
	s_addc_u32 s19, s85, 0
	s_mov_b32 s34, 1
	s_mov_b64 s[22:23], 0
	v_mov_b32_e32 v0, 0
	s_branch .LBB0_350

; __device__ __forceinline__ unsigned xb_ld(unsigned* p)              { return __hip_atomic_load(p, __ATOMIC_RELAXED, __HIP_MEMORY_SCOPE_AGENT); }
; __device__ __forceinline__ unsigned xb_add(unsigned* p, unsigned v) { return __hip_atomic_fetch_add(p, v, __ATOMIC_RELAXED, __HIP_MEMORY_SCOPE_AGENT); }
; #define XB_SPIN(cond, bar) do { unsigned _sp = 0; while (cond) { __builtin_amdgcn_s_sleep(1); \
;     if ((++_sp & 255u) == 0u) { if (xb_ld(&(bar)[XB_TMO])) break; if (_sp > XB_SPIN_CAP) { atomicAdd(&(bar)[XB_TMO], 1u); break; } } } } while (0)
; __device__ __forceinline__ void xcd_barrier(const XcdBarrier& b) {
;     ...
;         const unsigned old = xb_add(&bar[XB_XSUB(b.x)], 1u);
;         const unsigned gen = old / nloc;
;         if (old + 1u == (gen + 1u) * nloc) {
;             __builtin_amdgcn_fence(__ATOMIC_RELEASE, "agent");
;             asm volatile("s_waitcnt vmcnt(0)" ::: "memory");
;             const unsigned og = xb_add(&bar[XB_TOP], 1u);
;             const unsigned tg = og / nx;
;             if (og + 1u == (tg + 1u) * nx) xb_add(&bar[XB_TOPGEN], 1u);
;             else XB_SPIN(xb_ld(&bar[XB_TOPGEN]) == tg, bar);
;             __builtin_amdgcn_fence(__ATOMIC_ACQUIRE, "agent");
;             xb_add(&bar[XB_XGEN(b.x)], 1u);
;             asm volatile("s_waitcnt vmcnt(0)" ::: "memory");
;         } else {
;             XB_SPIN(xb_ld(&bar[XB_XGEN(b.x)]) == gen, bar);
.LBB0_529:
	s_lshl_b32 s8, s65, 8
	s_add_u32 s8, s88, s8
	s_addc_u32 s9, s89, 0
	v_mov_b32_e32 v1, 0x1000
	v_mov_b32_e32 v3, 1
	global_atomic_add v3, v1, v3, s[8:9] offset:1024 sc0
	v_cvt_f32_u32_e32 v1, v2
	v_sub_u32_e32 v4, 0, v2
	v_rcp_iflag_f32_e32 v1, v1
	s_nop 0
	v_mul_f32_e32 v1, 0x4f7ffffe, v1
	v_cvt_u32_f32_e32 v1, v1
	v_mul_lo_u32 v4, v4, v1
	v_mul_hi_u32 v4, v1, v4
	v_add_u32_e32 v1, v1, v4
	s_waitcnt vmcnt(0)
	v_mul_hi_u32 v1, v3, v1
	v_mul_lo_u32 v4, v1, v2
	v_sub_u32_e32 v4, v3, v4
	v_add_u32_e32 v5, 1, v1
	v_cmp_ge_u32_e32 vcc, v4, v2
	v_add_u32_e32 v3, 1, v3
	s_nop 0
	v_cndmask_b32_e32 v1, v1, v5, vcc
	v_sub_u32_e32 v5, v4, v2
	v_cndmask_b32_e32 v4, v4, v5, vcc
	v_add_u32_e32 v5, 1, v1
	v_cmp_ge_u32_e32 vcc, v4, v2
	s_nop 1
	v_cndmask_b32_e32 v1, v1, v5, vcc
	v_mul_lo_u32 v4, v2, v1
	v_add_u32_e32 v2, v4, v2
	v_cmp_ne_u32_e32 vcc, v3, v2
	s_and_saveexec_b64 s[10:11], vcc
	s_xor_b64 s[10:11], exec, s[10:11]
	s_cbranch_execz .LBB0_543
	s_waitcnt lgkmcnt(0)
	s_lshl_b32 s98, s65, 8
	s_sub_u32 s22, s8, s98
	s_subb_u32 s23, s9, 0
	s_add_u32 s22, s22, 0x3500
	s_addc_u32 s23, s23, 0
	v_mov_b32_e32 v0, 0
	global_load_dword v0, v0, s[22:23] sc1
	s_waitcnt vmcnt(0)
	v_cmp_eq_u32_e32 vcc, v0, v1
	s_and_saveexec_b64 s[18:19], vcc
	s_cbranch_execz .LBB0_542
	s_add_u32 s20, s84, 0xc0200
	s_addc_u32 s21, s85, 0
	s_mov_b32 s36, 1
	s_mov_b64 s[24:25], 0
	v_mov_b32_e32 v0, 0
	s_branch .LBB0_533

; __device__ __forceinline__ unsigned xb_ld(unsigned* p)              { return __hip_atomic_load(p, __ATOMIC_RELAXED, __HIP_MEMORY_SCOPE_AGENT); }
; __device__ __forceinline__ unsigned xb_add(unsigned* p, unsigned v) { return __hip_atomic_fetch_add(p, v, __ATOMIC_RELAXED, __HIP_MEMORY_SCOPE_AGENT); }
; #define XB_SPIN(cond, bar) do { unsigned _sp = 0; while (cond) { __builtin_amdgcn_s_sleep(1); \
;     if ((++_sp & 255u) == 0u) { if (xb_ld(&(bar)[XB_TMO])) break; if (_sp > XB_SPIN_CAP) { atomicAdd(&(bar)[XB_TMO], 1u); break; } } } } while (0)
; __device__ __forceinline__ void xcd_barrier(const XcdBarrier& b) {
;     ...
;         const unsigned old = xb_add(&bar[XB_XSUB(b.x)], 1u);
;         const unsigned gen = old / nloc;
;         if (old + 1u == (gen + 1u) * nloc) {
;             __builtin_amdgcn_fence(__ATOMIC_RELEASE, "agent");
;             asm volatile("s_waitcnt vmcnt(0)" ::: "memory");
;             const unsigned og = xb_add(&bar[XB_TOP], 1u);
;             const unsigned tg = og / nx;
;             if (og + 1u == (tg + 1u) * nx) xb_add(&bar[XB_TOPGEN], 1u);
;             else XB_SPIN(xb_ld(&bar[XB_TOPGEN]) == tg, bar);
;             __builtin_amdgcn_fence(__ATOMIC_ACQUIRE, "agent");
;             xb_add(&bar[XB_XGEN(b.x)], 1u);
;             asm volatile("s_waitcnt vmcnt(0)" ::: "memory");
;         } else {
;             XB_SPIN(xb_ld(&bar[XB_XGEN(b.x)]) == gen, bar);
.LBB0_598:
	s_lshl_b32 s6, s65, 8
	s_add_u32 s6, s88, s6
	s_addc_u32 s7, s89, 0
	v_mov_b32_e32 v1, 0x1000
	v_mov_b32_e32 v3, 1
	global_atomic_add v3, v1, v3, s[6:7] offset:1024 sc0
	v_cvt_f32_u32_e32 v1, v2
	v_sub_u32_e32 v4, 0, v2
	v_rcp_iflag_f32_e32 v1, v1
	s_nop 0
	v_mul_f32_e32 v1, 0x4f7ffffe, v1
	v_cvt_u32_f32_e32 v1, v1
	v_mul_lo_u32 v4, v4, v1
	v_mul_hi_u32 v4, v1, v4
	v_add_u32_e32 v1, v1, v4
	s_waitcnt vmcnt(0)
	v_mul_hi_u32 v1, v3, v1
	v_mul_lo_u32 v4, v1, v2
	v_sub_u32_e32 v4, v3, v4
	v_add_u32_e32 v5, 1, v1
	v_cmp_ge_u32_e32 vcc, v4, v2
	v_add_u32_e32 v3, 1, v3
	s_nop 0
	v_cndmask_b32_e32 v1, v1, v5, vcc
	v_sub_u32_e32 v5, v4, v2
	v_cndmask_b32_e32 v4, v4, v5, vcc
	v_add_u32_e32 v5, 1, v1
	v_cmp_ge_u32_e32 vcc, v4, v2
	s_nop 1
	v_cndmask_b32_e32 v1, v1, v5, vcc
	v_mul_lo_u32 v4, v2, v1
	v_add_u32_e32 v2, v4, v2
	v_cmp_ne_u32_e32 vcc, v3, v2
	s_and_saveexec_b64 s[8:9], vcc
	s_xor_b64 s[8:9], exec, s[8:9]
	s_cbranch_execz .LBB0_612
	s_waitcnt lgkmcnt(0)
	s_lshl_b32 s98, s65, 8
	s_sub_u32 s22, s6, s98
	s_subb_u32 s23, s7, 0
	s_add_u32 s22, s22, 0x3500
	s_addc_u32 s23, s23, 0
	v_mov_b32_e32 v0, 0
	global_load_dword v0, v0, s[22:23] sc1
	s_waitcnt vmcnt(0)
	v_cmp_eq_u32_e32 vcc, v0, v1
	s_and_saveexec_b64 s[10:11], vcc
	s_cbranch_execz .LBB0_611
	s_add_u32 s20, s84, 0xc0200
	s_addc_u32 s21, s85, 0
	s_mov_b32 s36, 1
	s_mov_b64 s[24:25], 0
	v_mov_b32_e32 v0, 0
	s_branch .LBB0_602

; __device__ __forceinline__ unsigned xb_ld(unsigned* p)              { return __hip_atomic_load(p, __ATOMIC_RELAXED, __HIP_MEMORY_SCOPE_AGENT); }
; __device__ __forceinline__ unsigned xb_add(unsigned* p, unsigned v) { return __hip_atomic_fetch_add(p, v, __ATOMIC_RELAXED, __HIP_MEMORY_SCOPE_AGENT); }
; #define XB_SPIN(cond, bar) do { unsigned _sp = 0; while (cond) { __builtin_amdgcn_s_sleep(1); \
;     if ((++_sp & 255u) == 0u) { if (xb_ld(&(bar)[XB_TMO])) break; if (_sp > XB_SPIN_CAP) { atomicAdd(&(bar)[XB_TMO], 1u); break; } } } } while (0)
; __device__ __forceinline__ void xcd_barrier(const XcdBarrier& b) {
;     ...
;         const unsigned old = xb_add(&bar[XB_XSUB(b.x)], 1u);
;         const unsigned gen = old / nloc;
;         if (old + 1u == (gen + 1u) * nloc) {
;             __builtin_amdgcn_fence(__ATOMIC_RELEASE, "agent");
;             asm volatile("s_waitcnt vmcnt(0)" ::: "memory");
;             const unsigned og = xb_add(&bar[XB_TOP], 1u);
;             const unsigned tg = og / nx;
;             if (og + 1u == (tg + 1u) * nx) xb_add(&bar[XB_TOPGEN], 1u);
;             else XB_SPIN(xb_ld(&bar[XB_TOPGEN]) == tg, bar);
;             __builtin_amdgcn_fence(__ATOMIC_ACQUIRE, "agent");
;             xb_add(&bar[XB_XGEN(b.x)], 1u);
;             asm volatile("s_waitcnt vmcnt(0)" ::: "memory");
;         } else {
;             XB_SPIN(xb_ld(&bar[XB_XGEN(b.x)]) == gen, bar);
.LBB0_683:
	s_lshl_b32 s3, s65, 8
	s_add_u32 s6, s88, s3
	s_addc_u32 s7, s89, 0
	v_mov_b32_e32 v1, 0x1000
	v_mov_b32_e32 v3, 1
	global_atomic_add v3, v1, v3, s[6:7] offset:1024 sc0
	v_cvt_f32_u32_e32 v1, v2
	v_sub_u32_e32 v4, 0, v2
	v_rcp_iflag_f32_e32 v1, v1
	s_nop 0
	v_mul_f32_e32 v1, 0x4f7ffffe, v1
	v_cvt_u32_f32_e32 v1, v1
	v_mul_lo_u32 v4, v4, v1
	v_mul_hi_u32 v4, v1, v4
	v_add_u32_e32 v1, v1, v4
	s_waitcnt vmcnt(0)
	v_mul_hi_u32 v1, v3, v1
	v_mul_lo_u32 v4, v1, v2
	v_sub_u32_e32 v4, v3, v4
	v_add_u32_e32 v5, 1, v1
	v_cmp_ge_u32_e32 vcc, v4, v2
	v_add_u32_e32 v3, 1, v3
	s_nop 0
	v_cndmask_b32_e32 v1, v1, v5, vcc
	v_sub_u32_e32 v5, v4, v2
	v_cndmask_b32_e32 v4, v4, v5, vcc
	v_add_u32_e32 v5, 1, v1
	v_cmp_ge_u32_e32 vcc, v4, v2
	s_nop 1
	v_cndmask_b32_e32 v1, v1, v5, vcc
	v_mul_lo_u32 v4, v2, v1
	v_add_u32_e32 v2, v4, v2
	v_cmp_ne_u32_e32 vcc, v3, v2
	s_and_saveexec_b64 s[8:9], vcc
	s_xor_b64 s[8:9], exec, s[8:9]
	s_cbranch_execz .LBB0_697
	s_waitcnt lgkmcnt(0)
	s_lshl_b32 s98, s65, 8
	s_sub_u32 s24, s6, s98
	s_subb_u32 s25, s7, 0
	s_add_u32 s24, s24, 0x3500
	s_addc_u32 s25, s25, 0
	v_mov_b32_e32 v0, 0
	global_load_dword v0, v0, s[24:25] sc1
	s_waitcnt vmcnt(0)
	v_cmp_eq_u32_e32 vcc, v0, v1
	s_and_saveexec_b64 s[10:11], vcc
	s_cbranch_execz .LBB0_696
	s_add_u32 s22, s84, 0xc0200
	s_addc_u32 s23, s85, 0
	s_mov_b32 s3, 1
	s_mov_b64 s[26:27], 0
	v_mov_b32_e32 v0, 0
	s_branch .LBB0_687

; __device__ __forceinline__ unsigned xb_ld(unsigned* p)              { return __hip_atomic_load(p, __ATOMIC_RELAXED, __HIP_MEMORY_SCOPE_AGENT); }
; __device__ __forceinline__ unsigned xb_add(unsigned* p, unsigned v) { return __hip_atomic_fetch_add(p, v, __ATOMIC_RELAXED, __HIP_MEMORY_SCOPE_AGENT); }
; #define XB_SPIN(cond, bar) do { unsigned _sp = 0; while (cond) { __builtin_amdgcn_s_sleep(1); \
;     if ((++_sp & 255u) == 0u) { if (xb_ld(&(bar)[XB_TMO])) break; if (_sp > XB_SPIN_CAP) { atomicAdd(&(bar)[XB_TMO], 1u); break; } } } } while (0)
; __device__ __forceinline__ void xcd_barrier(const XcdBarrier& b) {
;     ...
;         const unsigned old = xb_add(&bar[XB_XSUB(b.x)], 1u);
;         const unsigned gen = old / nloc;
;         if (old + 1u == (gen + 1u) * nloc) {
;             __builtin_amdgcn_fence(__ATOMIC_RELEASE, "agent");
;             asm volatile("s_waitcnt vmcnt(0)" ::: "memory");
;             const unsigned og = xb_add(&bar[XB_TOP], 1u);
;             const unsigned tg = og / nx;
;             if (og + 1u == (tg + 1u) * nx) xb_add(&bar[XB_TOPGEN], 1u);
;             else XB_SPIN(xb_ld(&bar[XB_TOPGEN]) == tg, bar);
;             __builtin_amdgcn_fence(__ATOMIC_ACQUIRE, "agent");
;             xb_add(&bar[XB_XGEN(b.x)], 1u);
;             asm volatile("s_waitcnt vmcnt(0)" ::: "memory");
;         } else {
;             XB_SPIN(xb_ld(&bar[XB_XGEN(b.x)]) == gen, bar);
.LBB0_907:
	s_lshl_b32 s6, s65, 8
	s_add_u32 s6, s88, s6
	s_addc_u32 s7, s89, 0
	v_mov_b32_e32 v1, 0x1000
	v_mov_b32_e32 v3, 1
	global_atomic_add v3, v1, v3, s[6:7] offset:1024 sc0
	v_cvt_f32_u32_e32 v1, v2
	v_sub_u32_e32 v4, 0, v2
	v_rcp_iflag_f32_e32 v1, v1
	s_nop 0
	v_mul_f32_e32 v1, 0x4f7ffffe, v1
	v_cvt_u32_f32_e32 v1, v1
	v_mul_lo_u32 v4, v4, v1
	v_mul_hi_u32 v4, v1, v4
	v_add_u32_e32 v1, v1, v4
	s_waitcnt vmcnt(0)
	v_mul_hi_u32 v1, v3, v1
	v_mul_lo_u32 v4, v1, v2
	v_sub_u32_e32 v4, v3, v4
	v_add_u32_e32 v5, 1, v1
	v_cmp_ge_u32_e32 vcc, v4, v2
	v_add_u32_e32 v3, 1, v3
	s_nop 0
	v_cndmask_b32_e32 v1, v1, v5, vcc
	v_sub_u32_e32 v5, v4, v2
	v_cndmask_b32_e32 v4, v4, v5, vcc
	v_add_u32_e32 v5, 1, v1
	v_cmp_ge_u32_e32 vcc, v4, v2
	s_nop 1
	v_cndmask_b32_e32 v1, v1, v5, vcc
	v_mul_lo_u32 v4, v2, v1
	v_add_u32_e32 v2, v4, v2
	v_cmp_ne_u32_e32 vcc, v3, v2
	s_and_saveexec_b64 s[8:9], vcc
	s_xor_b64 s[8:9], exec, s[8:9]
	s_cbranch_execz .LBB0_921
	s_waitcnt lgkmcnt(0)
	s_lshl_b32 s98, s65, 8
	s_sub_u32 s26, s6, s98
	s_subb_u32 s27, s7, 0
	s_add_u32 s26, s26, 0x3500
	s_addc_u32 s27, s27, 0
	v_mov_b32_e32 v0, 0
	global_load_dword v0, v0, s[26:27] sc1
	s_waitcnt vmcnt(0)
	v_cmp_eq_u32_e32 vcc, v0, v1
	s_and_saveexec_b64 s[10:11], vcc
	s_cbranch_execz .LBB0_920
	s_add_u32 s24, s84, 0xc0200
	s_addc_u32 s25, s85, 0
	s_mov_b32 s40, 1
	s_mov_b64 s[28:29], 0
	v_mov_b32_e32 v0, 0
	s_branch .LBB0_911

; __device__ __forceinline__ unsigned xb_ld(unsigned* p)              { return __hip_atomic_load(p, __ATOMIC_RELAXED, __HIP_MEMORY_SCOPE_AGENT); }
; __device__ __forceinline__ unsigned xb_add(unsigned* p, unsigned v) { return __hip_atomic_fetch_add(p, v, __ATOMIC_RELAXED, __HIP_MEMORY_SCOPE_AGENT); }
; #define XB_SPIN(cond, bar) do { unsigned _sp = 0; while (cond) { __builtin_amdgcn_s_sleep(1); \
;     if ((++_sp & 255u) == 0u) { if (xb_ld(&(bar)[XB_TMO])) break; if (_sp > XB_SPIN_CAP) { atomicAdd(&(bar)[XB_TMO], 1u); break; } } } } while (0)
; __device__ __forceinline__ void xcd_barrier(const XcdBarrier& b) {
;     ...
;         const unsigned old = xb_add(&bar[XB_XSUB(b.x)], 1u);
;         const unsigned gen = old / nloc;
;         if (old + 1u == (gen + 1u) * nloc) {
;             __builtin_amdgcn_fence(__ATOMIC_RELEASE, "agent");
;             asm volatile("s_waitcnt vmcnt(0)" ::: "memory");
;             const unsigned og = xb_add(&bar[XB_TOP], 1u);
;             const unsigned tg = og / nx;
;             if (og + 1u == (tg + 1u) * nx) xb_add(&bar[XB_TOPGEN], 1u);
;             else XB_SPIN(xb_ld(&bar[XB_TOPGEN]) == tg, bar);
;             __builtin_amdgcn_fence(__ATOMIC_ACQUIRE, "agent");
;             xb_add(&bar[XB_XGEN(b.x)], 1u);
;             asm volatile("s_waitcnt vmcnt(0)" ::: "memory");
;         } else {
;             XB_SPIN(xb_ld(&bar[XB_XGEN(b.x)]) == gen, bar);
.LBB0_1024:
	s_lshl_b32 s6, s65, 8
	s_add_u32 s6, s88, s6
	s_addc_u32 s7, s89, 0
	v_mov_b32_e32 v1, 0x1000
	v_mov_b32_e32 v3, 1
	global_atomic_add v3, v1, v3, s[6:7] offset:1024 sc0
	v_cvt_f32_u32_e32 v1, v2
	v_sub_u32_e32 v4, 0, v2
	v_rcp_iflag_f32_e32 v1, v1
	s_nop 0
	v_mul_f32_e32 v1, 0x4f7ffffe, v1
	v_cvt_u32_f32_e32 v1, v1
	v_mul_lo_u32 v4, v4, v1
	v_mul_hi_u32 v4, v1, v4
	v_add_u32_e32 v1, v1, v4
	s_waitcnt vmcnt(0)
	v_mul_hi_u32 v1, v3, v1
	v_mul_lo_u32 v4, v1, v2
	v_sub_u32_e32 v4, v3, v4
	v_add_u32_e32 v5, 1, v1
	v_cmp_ge_u32_e32 vcc, v4, v2
	v_add_u32_e32 v3, 1, v3
	s_nop 0
	v_cndmask_b32_e32 v1, v1, v5, vcc
	v_sub_u32_e32 v5, v4, v2
	v_cndmask_b32_e32 v4, v4, v5, vcc
	v_add_u32_e32 v5, 1, v1
	v_cmp_ge_u32_e32 vcc, v4, v2
	s_nop 1
	v_cndmask_b32_e32 v1, v1, v5, vcc
	v_mul_lo_u32 v4, v2, v1
	v_add_u32_e32 v2, v4, v2
	v_cmp_ne_u32_e32 vcc, v3, v2
	s_and_saveexec_b64 s[8:9], vcc
	s_xor_b64 s[8:9], exec, s[8:9]
	s_cbranch_execz .LBB0_1038
	s_waitcnt lgkmcnt(0)
	s_lshl_b32 s98, s65, 8
	s_sub_u32 s24, s6, s98
	s_subb_u32 s25, s7, 0
	s_add_u32 s24, s24, 0x3500
	s_addc_u32 s25, s25, 0
	v_mov_b32_e32 v0, 0
	global_load_dword v0, v0, s[24:25] sc1
	s_waitcnt vmcnt(0)
	v_cmp_eq_u32_e32 vcc, v0, v1
	s_and_saveexec_b64 s[10:11], vcc
	s_cbranch_execz .LBB0_1037
	s_add_u32 s22, s84, 0xc0200
	s_addc_u32 s23, s85, 0
	s_mov_b32 s38, 1
	s_mov_b64 s[26:27], 0
	v_mov_b32_e32 v0, 0
	s_branch .LBB0_1028

; __device__ __forceinline__ unsigned xb_ld(unsigned* p)              { return __hip_atomic_load(p, __ATOMIC_RELAXED, __HIP_MEMORY_SCOPE_AGENT); }
; __device__ __forceinline__ unsigned xb_add(unsigned* p, unsigned v) { return __hip_atomic_fetch_add(p, v, __ATOMIC_RELAXED, __HIP_MEMORY_SCOPE_AGENT); }
; #define XB_SPIN(cond, bar) do { unsigned _sp = 0; while (cond) { __builtin_amdgcn_s_sleep(1); \
;     if ((++_sp & 255u) == 0u) { if (xb_ld(&(bar)[XB_TMO])) break; if (_sp > XB_SPIN_CAP) { atomicAdd(&(bar)[XB_TMO], 1u); break; } } } } while (0)
; __device__ __forceinline__ void xcd_barrier(const XcdBarrier& b) {
;     ...
;         const unsigned old = xb_add(&bar[XB_XSUB(b.x)], 1u);
;         const unsigned gen = old / nloc;
;         if (old + 1u == (gen + 1u) * nloc) {
;             __builtin_amdgcn_fence(__ATOMIC_RELEASE, "agent");
;             asm volatile("s_waitcnt vmcnt(0)" ::: "memory");
;             const unsigned og = xb_add(&bar[XB_TOP], 1u);
;             const unsigned tg = og / nx;
;             if (og + 1u == (tg + 1u) * nx) xb_add(&bar[XB_TOPGEN], 1u);
;             else XB_SPIN(xb_ld(&bar[XB_TOPGEN]) == tg, bar);
;             __builtin_amdgcn_fence(__ATOMIC_ACQUIRE, "agent");
;             xb_add(&bar[XB_XGEN(b.x)], 1u);
;             asm volatile("s_waitcnt vmcnt(0)" ::: "memory");
;         } else {
;             XB_SPIN(xb_ld(&bar[XB_XGEN(b.x)]) == gen, bar);
.LBB0_1180:
	s_lshl_b32 s3, s65, 8
	s_add_u32 s6, s88, s3
	s_addc_u32 s7, s89, 0
	v_mov_b32_e32 v1, 0x1000
	v_mov_b32_e32 v3, 1
	global_atomic_add v3, v1, v3, s[6:7] offset:1024 sc0
	v_cvt_f32_u32_e32 v1, v2
	v_sub_u32_e32 v4, 0, v2
	v_rcp_iflag_f32_e32 v1, v1
	s_nop 0
	v_mul_f32_e32 v1, 0x4f7ffffe, v1
	v_cvt_u32_f32_e32 v1, v1
	v_mul_lo_u32 v4, v4, v1
	v_mul_hi_u32 v4, v1, v4
	v_add_u32_e32 v1, v1, v4
	s_waitcnt vmcnt(0)
	v_mul_hi_u32 v1, v3, v1
	v_mul_lo_u32 v4, v1, v2
	v_sub_u32_e32 v4, v3, v4
	v_add_u32_e32 v5, 1, v1
	v_cmp_ge_u32_e32 vcc, v4, v2
	v_add_u32_e32 v3, 1, v3
	s_nop 0
	v_cndmask_b32_e32 v1, v1, v5, vcc
	v_sub_u32_e32 v5, v4, v2
	v_cndmask_b32_e32 v4, v4, v5, vcc
	v_add_u32_e32 v5, 1, v1
	v_cmp_ge_u32_e32 vcc, v4, v2
	s_nop 1
	v_cndmask_b32_e32 v1, v1, v5, vcc
	v_mul_lo_u32 v4, v2, v1
	v_add_u32_e32 v2, v4, v2
	v_cmp_ne_u32_e32 vcc, v3, v2
	s_and_saveexec_b64 s[8:9], vcc
	s_xor_b64 s[8:9], exec, s[8:9]
	s_cbranch_execz .LBB0_1194
	s_waitcnt lgkmcnt(0)
	s_lshl_b32 s98, s65, 8
	s_sub_u32 s14, s6, s98
	s_subb_u32 s15, s7, 0
	s_add_u32 s14, s14, 0x3500
	s_addc_u32 s15, s15, 0
	v_mov_b32_e32 v0, 0
	global_load_dword v0, v0, s[14:15] sc1
	s_waitcnt vmcnt(0)
	v_cmp_eq_u32_e32 vcc, v0, v1
	s_and_saveexec_b64 s[10:11], vcc
	s_cbranch_execz .LBB0_1193
	s_add_u32 s12, s84, 0xc0200
	s_addc_u32 s13, s85, 0
	s_mov_b32 s3, 1
	s_mov_b64 s[16:17], 0
	v_mov_b32_e32 v0, 0
	s_branch .LBB0_1184

; __device__ __forceinline__ unsigned xb_ld(unsigned* p)              { return __hip_atomic_load(p, __ATOMIC_RELAXED, __HIP_MEMORY_SCOPE_AGENT); }
; __device__ __forceinline__ unsigned xb_add(unsigned* p, unsigned v) { return __hip_atomic_fetch_add(p, v, __ATOMIC_RELAXED, __HIP_MEMORY_SCOPE_AGENT); }
; #define XB_SPIN(cond, bar) do { unsigned _sp = 0; while (cond) { __builtin_amdgcn_s_sleep(1); \
;     if ((++_sp & 255u) == 0u) { if (xb_ld(&(bar)[XB_TMO])) break; if (_sp > XB_SPIN_CAP) { atomicAdd(&(bar)[XB_TMO], 1u); break; } } } } while (0)
; __device__ __forceinline__ void xcd_barrier(const XcdBarrier& b) {
;     ...
;         const unsigned old = xb_add(&bar[XB_XSUB(b.x)], 1u);
;         const unsigned gen = old / nloc;
;         if (old + 1u == (gen + 1u) * nloc) {
;             __builtin_amdgcn_fence(__ATOMIC_RELEASE, "agent");
;             asm volatile("s_waitcnt vmcnt(0)" ::: "memory");
;             const unsigned og = xb_add(&bar[XB_TOP], 1u);
;             const unsigned tg = og / nx;
;             if (og + 1u == (tg + 1u) * nx) xb_add(&bar[XB_TOPGEN], 1u);
;             else XB_SPIN(xb_ld(&bar[XB_TOPGEN]) == tg, bar);
;             __builtin_amdgcn_fence(__ATOMIC_ACQUIRE, "agent");
;             xb_add(&bar[XB_XGEN(b.x)], 1u);
;             asm volatile("s_waitcnt vmcnt(0)" ::: "memory");
;         } else {
;             XB_SPIN(xb_ld(&bar[XB_XGEN(b.x)]) == gen, bar);
.LBB0_1255:
	s_lshl_b32 s4, s65, 8
	s_add_u32 s4, s88, s4
	s_addc_u32 s5, s89, 0
	v_mov_b32_e32 v1, 0x1000
	v_mov_b32_e32 v3, 1
	global_atomic_add v3, v1, v3, s[4:5] offset:1024 sc0
	v_cvt_f32_u32_e32 v1, v2
	v_sub_u32_e32 v4, 0, v2
	v_rcp_iflag_f32_e32 v1, v1
	s_nop 0
	v_mul_f32_e32 v1, 0x4f7ffffe, v1
	v_cvt_u32_f32_e32 v1, v1
	v_mul_lo_u32 v4, v4, v1
	v_mul_hi_u32 v4, v1, v4
	v_add_u32_e32 v1, v1, v4
	s_waitcnt vmcnt(0)
	v_mul_hi_u32 v1, v3, v1
	v_mul_lo_u32 v4, v1, v2
	v_sub_u32_e32 v4, v3, v4
	v_add_u32_e32 v5, 1, v1
	v_cmp_ge_u32_e32 vcc, v4, v2
	v_add_u32_e32 v3, 1, v3
	s_nop 0
	v_cndmask_b32_e32 v1, v1, v5, vcc
	v_sub_u32_e32 v5, v4, v2
	v_cndmask_b32_e32 v4, v4, v5, vcc
	v_add_u32_e32 v5, 1, v1
	v_cmp_ge_u32_e32 vcc, v4, v2
	s_nop 1
	v_cndmask_b32_e32 v1, v1, v5, vcc
	v_mul_lo_u32 v4, v2, v1
	v_add_u32_e32 v2, v4, v2
	v_cmp_ne_u32_e32 vcc, v3, v2
	s_and_saveexec_b64 s[6:7], vcc
	s_xor_b64 s[6:7], exec, s[6:7]
	s_cbranch_execz .LBB0_1269
	s_waitcnt lgkmcnt(0)
	s_lshl_b32 s98, s65, 8
	s_sub_u32 s12, s4, s98
	s_subb_u32 s13, s5, 0
	s_add_u32 s12, s12, 0x3500
	s_addc_u32 s13, s13, 0
	v_mov_b32_e32 v0, 0
	global_load_dword v0, v0, s[12:13] sc1
	s_waitcnt vmcnt(0)
	v_cmp_eq_u32_e32 vcc, v0, v1
	s_and_saveexec_b64 s[8:9], vcc
	s_cbranch_execz .LBB0_1268
	s_add_u32 s10, s84, 0xc0200
	s_addc_u32 s11, s85, 0
	s_mov_b32 s24, 1
	s_mov_b64 s[14:15], 0
	v_mov_b32_e32 v0, 0
	s_branch .LBB0_1259

; __global__ void __launch_bounds__(NWAVES * 64, 2) mk_fwd(Args args) {
	.amdhsa_kernel _Z6mk_fwd4Args
		.amdhsa_group_segment_fixed_size 0
		.amdhsa_private_segment_fixed_size 0
		.amdhsa_kernarg_size 432
		.amdhsa_user_sgpr_count 2
		.amdhsa_user_sgpr_dispatch_ptr 0
		.amdhsa_user_sgpr_queue_ptr 0
		.amdhsa_user_sgpr_kernarg_segment_ptr 1
		.amdhsa_user_sgpr_dispatch_id 0
		.amdhsa_user_sgpr_kernarg_preload_length 0
		.amdhsa_user_sgpr_kernarg_preload_offset 0
		.amdhsa_user_sgpr_private_segment_size 0
		.amdhsa_uses_dynamic_stack 0
		.amdhsa_enable_private_segment 0
		.amdhsa_system_sgpr_workgroup_id_x 1
		.amdhsa_system_sgpr_workgroup_id_y 0
		.amdhsa_system_sgpr_workgroup_id_z 0
		.amdhsa_system_sgpr_workgroup_info 0
		.amdhsa_system_vgpr_workitem_id 2
		.amdhsa_next_free_vgpr 248
		.amdhsa_next_free_sgpr 102
		.amdhsa_accum_offset 248
		.amdhsa_reserve_vcc 1
		.amdhsa_float_round_mode_32 0
		.amdhsa_float_round_mode_16_64 0
		.amdhsa_float_denorm_mode_32 3
		.amdhsa_float_denorm_mode_16_64 3
		.amdhsa_dx10_clamp 1
		.amdhsa_ieee_mode 1
		.amdhsa_fp16_overflow 0
		.amdhsa_tg_split 0
		.amdhsa_exception_fp_ieee_invalid_op 0
		.amdhsa_exception_fp_denorm_src 0
		.amdhsa_exception_fp_ieee_div_zero 0
		.amdhsa_exception_fp_ieee_overflow 0
		.amdhsa_exception_fp_ieee_underflow 0
		.amdhsa_exception_fp_ieee_inexact 0
		.amdhsa_exception_int_div_zero 0
	.end_amdhsa_kernel

; __global__ void __launch_bounds__(NWAVES * 64, 2) mk_fwd(Args args) {
amdhsa.kernels:
  - .agpr_count:     0
    .args:
      - .offset:         0
        .size:           176
        .value_kind:     by_value
      - .offset:         176
        .size:           4
        .value_kind:     hidden_block_count_x
      - .offset:         180
        .size:           4
        .value_kind:     hidden_block_count_y
      - .offset:         184
        .size:           4
        .value_kind:     hidden_block_count_z
      - .offset:         188
        .size:           2
        .value_kind:     hidden_group_size_x
      - .offset:         190
        .size:           2
        .value_kind:     hidden_group_size_y
      - .offset:         192
        .size:           2
        .value_kind:     hidden_group_size_z
      - .offset:         194
        .size:           2
        .value_kind:     hidden_remainder_x
      - .offset:         196
        .size:           2
        .value_kind:     hidden_remainder_y
      - .offset:         198
        .size:           2
        .value_kind:     hidden_remainder_z
      - .offset:         216
        .size:           8
        .value_kind:     hidden_global_offset_x
      - .offset:         224
        .size:           8
        .value_kind:     hidden_global_offset_y
      - .offset:         232
        .size:           8
        .value_kind:     hidden_global_offset_z
      - .offset:         240
        .size:           2
        .value_kind:     hidden_grid_dims
      - .offset:         264
        .size:           8
        .value_kind:     hidden_multigrid_sync_arg
      - .offset:         296
        .size:           4
        .value_kind:     hidden_dynamic_lds_size
    .group_segment_fixed_size: 0
    .kernarg_segment_align: 8
    .kernarg_segment_size: 432
    .language:       OpenCL C
    .language_version:
      - 2
      - 0
    .max_flat_workgroup_size: 512
    .name:           _Z6mk_fwd4Args
    .private_segment_fixed_size: 0
    .sgpr_count:     108
    .sgpr_spill_count: 78
    .symbol:         _Z6mk_fwd4Args.kd
    .uniform_work_group_size: 1
    .uses_dynamic_stack: false
    .vgpr_count:     248
    .vgpr_spill_count: 0
    .wavefront_size: 64
